# RET chain step: post-barrier-2 region rewritten (14 batched LDS reads, shared V fragments between intra-chunk and state update, no re-reads)
# speedup vs baseline: 1.0046x; 1.0008x over previous
; #define LAS __attribute__((address_space(3)))
; DI unsigned pk2(float lo, float hi) { const f32x2 v = {lo, hi}; const hbf16x2 b = __builtin_convertvector(v, hbf16x2); return __builtin_bit_cast(unsigned, b); }
; #define LDS_BARRIER() do { asm volatile("s_waitcnt lgkmcnt(0)" ::: "memory"); __builtin_amdgcn_s_barrier(); } while (0)
; #define MFMA16(a, b, c) __builtin_amdgcn_mfma_f32_16x16x32_bf16((a), (b), (c), 0, 0, 0)
; DI void ret_chain_phase(const Ctx& a, LAS unsigned char* lds) {
;     ...
;             LDS_BARRIER();
;             if (s + 1 < 68) RC_DMA_QK(s + 1);
; #pragma unroll
;             for (int vv = 0; vv < 2; ++vv) {
;                 const int vt = 2 * half + vv;
; #pragma unroll
;                 for (int k2 = 0; k2 < 2; ++k2) {
;                     const bf16x8 vf = *(const LAS bf16x8*)(lds + A128(RC_SVT, vt, k2));
;                     const bf16x8 pf = *(const LAS bf16x8*)(lds + A128(RC_SP, it, k2));
;                     accO[vv] = MFMA16(vf, pf, accO[vv]);
;                 }
;                 u32x2 w; w.x = pk2(accO[vv][0], accO[vv][1]); w.y = pk2(accO[vv][2], accO[vv][3]);
;                 *(u32x2*)(O + (size_t)(row0 + icol) * 2048 + h * 512 + vs * 64 + 16 * vt + 4 * fq) = w;
;             }
;             bf16x8 vfr[4][2];
; #pragma unroll
;             for (int vt = 0; vt < 4; ++vt) { vfr[vt][0] = *(const LAS bf16x8*)(lds + A128(RC_SVT, vt, 0)); vfr[vt][1] = *(const LAS bf16x8*)(lds + A128(RC_SVT, vt, 1)); }
; #pragma unroll
;             for (int di = 0; di < 2; ++di) {
;                 const int dt = 2 * wid + di;
;                 bf16x8 kt[2];
; #pragma unroll
;                 for (int k2 = 0; k2 < 2; ++k2) kt[k2] = *(const LAS bf16x8*)(lds + A128(RC_SKT, dt, k2));
; #pragma unroll
;                 for (int vt = 0; vt < 4; ++vt) {
;                     f32x4 sacc = accS[di][vt] * cdec;
;                     sacc = MFMA16(kt[0], vfr[vt][0], sacc); sacc = MFMA16(kt[1], vfr[vt][1], sacc);
;                     accS[di][vt] = sacc;
;                     const int v_ = 16 * vt + fr;
;                     u32x2 w; w.x = pk2(sacc[0], sacc[1]); w.y = pk2(sacc[2], sacc[3]);
;                     *(LAS u32x2*)(lds + RC_SS + v_ * 512 + (((2 * dt + (fq >> 1)) ^ (v_ & 15)) << 4) + (fq & 1) * 8) = w;
;                 }
;             }
.LBB0_211:
	s_lshl_b32 s20, s30, 6
	s_add_i32 s20, s20, s31
	s_ashr_i32 s21, s20, 31
	s_lshl_b64 s[20:21], s[20:21], 11
	v_lshl_add_u64 v[60:61], s[20:21], 0, v[116:117]
	v_readfirstlane_b32 s20, v172
	v_lshl_add_u64 v[62:63], s[76:77], 0, v[60:61]
	s_mov_b32 m0, s20
	v_readfirstlane_b32 s20, v187
	v_lshl_add_u64 v[60:61], s[80:81], 0, v[60:61]
	global_load_lds_dwordx4 v[62:63], off
	s_mov_b32 m0, s20
	v_readfirstlane_b32 s20, v188
	global_load_lds_dwordx4 v[60:61], off
	v_lshl_add_u64 v[64:65], v[62:63], 0, s[52:53]
	s_mov_b32 m0, s20
	v_readfirstlane_b32 s20, v189
	global_load_lds_dwordx4 v[64:65], off
	v_lshl_add_u64 v[64:65], v[60:61], 0, s[52:53]
	s_mov_b32 m0, s20
	v_readfirstlane_b32 s20, v190
	global_load_lds_dwordx4 v[64:65], off
	v_lshl_add_u64 v[64:65], v[62:63], 0, s[28:29]
	s_mov_b32 m0, s20
	v_readfirstlane_b32 s20, v191
	global_load_lds_dwordx4 v[64:65], off
	v_lshl_add_u64 v[64:65], v[60:61], 0, s[28:29]
	s_mov_b32 m0, s20
	v_readfirstlane_b32 s20, v192
	global_load_lds_dwordx4 v[64:65], off
	v_lshl_add_u64 v[62:63], v[62:63], 0, s[68:69]
	s_mov_b32 m0, s20
	v_readfirstlane_b32 s20, v193
	global_load_lds_dwordx4 v[62:63], off
	v_lshl_add_u64 v[60:61], v[60:61], 0, s[68:69]
	s_mov_b32 m0, s20
	v_lshrrev_b32_e32 v68, 1, v105
	global_load_lds_dwordx4 v[60:61], off
	v_add_u32_e32 v60, s50, v122
	v_ashrrev_i32_e32 v61, 31, v60
	v_lshlrev_b64 v[60:61], 12, v[60:61]
	v_lshl_add_u64 v[198:199], v[108:109], 0, v[60:61]
	v_lshlrev_b32_e32 v208, 7, v105
	v_bitop3_b32 v60, v68, v121, 7 bitop3:0x6c
	v_lshlrev_b32_e32 v209, 4, v60
	v_bitop3_b32 v60, v68, v129, 7 bitop3:0x6c
	v_lshlrev_b32_e32 v219, 4, v60
	v_pk_mul_f32 v[58:59], v[112:113], v[86:87]
	v_pk_mul_f32 v[56:57], v[110:111], v[84:85]
	v_pk_mul_f32 v[54:55], v[112:113], v[54:55]
	v_pk_mul_f32 v[52:53], v[110:111], v[52:53]
	v_add3_u32 v250, v128, v208, v209
	ds_read_b128 v[64:67], v250
	v_add3_u32 v250, v128, v208, v219
	ds_read_b128 v[68:71], v250
	v_add3_u32 v250, s2, v208, v209
	ds_read_b128 v[60:63], v250
	v_add3_u32 v250, s2, v208, v219
	ds_read_b128 v[72:75], v250
	v_add3_u32 v250, s84, v208, v209
	ds_read_b128 v[76:79], v250
	v_add3_u32 v250, s84, v208, v219
	ds_read_b128 v[80:83], v250
	v_add3_u32 v250, s85, v208, v209
	ds_read_b128 v[230:233], v250
	v_add3_u32 v250, s85, v208, v219
	ds_read_b128 v[234:237], v250
	v_add3_u32 v250, s24, v208, v209
	ds_read_b128 v[238:241], v250
	v_add3_u32 v250, s24, v208, v219
	ds_read_b128 v[242:245], v250
	v_add3_u32 v250, v168, v208, v209
	ds_read_b128 v[246:249], v250
	v_add3_u32 v250, v168, v208, v219
	ds_read_b128 v[194:197], v250
	v_add3_u32 v250, v169, v208, v209
	ds_read_b128 v[222:225], v250
	v_add3_u32 v250, v169, v208, v219
	ds_read_b128 v[84:87], v250
	v_mov_b32_e32 v105, v104
	v_readfirstlane_b32 s20, v200
	v_pk_mul_f32 v[0:1], v[104:105], v[0:1]
	v_pk_mul_f32 v[2:3], v[104:105], v[2:3]
	v_pk_mul_f32 v[4:5], v[104:105], v[4:5]
	v_pk_mul_f32 v[6:7], v[104:105], v[6:7]
	v_pk_mul_f32 v[8:9], v[104:105], v[8:9]
	v_pk_mul_f32 v[10:11], v[104:105], v[10:11]
	v_pk_mul_f32 v[12:13], v[104:105], v[12:13]
	v_pk_mul_f32 v[14:15], v[104:105], v[14:15]
	v_pk_mul_f32 v[16:17], v[104:105], v[16:17]
	v_pk_mul_f32 v[18:19], v[104:105], v[18:19]
	v_pk_mul_f32 v[20:21], v[104:105], v[20:21]
	v_pk_mul_f32 v[22:23], v[104:105], v[22:23]
	v_pk_mul_f32 v[24:25], v[104:105], v[24:25]
	v_pk_mul_f32 v[26:27], v[104:105], v[26:27]
	v_pk_mul_f32 v[28:29], v[104:105], v[28:29]
	v_pk_mul_f32 v[30:31], v[104:105], v[30:31]
	s_cmp_lt_u32 s20, 0x100
	s_cbranch_scc0 .Lrc_h1
	s_waitcnt lgkmcnt(8)
	v_mfma_f32_16x16x32_bf16 v[56:59], v[60:63], v[64:67], v[56:59]
	v_mfma_f32_16x16x32_bf16 v[56:59], v[72:75], v[68:71], v[56:59]
	v_mfma_f32_16x16x32_bf16 v[52:55], v[76:79], v[64:67], v[52:55]
	v_mfma_f32_16x16x32_bf16 v[52:55], v[80:83], v[68:71], v[52:55]
	s_branch .Lrc_hj
.Lrc_h1:
	s_waitcnt lgkmcnt(4)
	v_mfma_f32_16x16x32_bf16 v[56:59], v[230:233], v[64:67], v[56:59]
	v_mfma_f32_16x16x32_bf16 v[56:59], v[234:237], v[68:71], v[56:59]
	v_mfma_f32_16x16x32_bf16 v[52:55], v[238:241], v[64:67], v[52:55]
	v_mfma_f32_16x16x32_bf16 v[52:55], v[242:245], v[68:71], v[52:55]
.Lrc_hj:
	s_waitcnt lgkmcnt(0)
	v_mfma_f32_16x16x32_bf16 v[8:11], v[246:249], v[60:63], v[8:11]
	v_mfma_f32_16x16x32_bf16 v[28:31], v[246:249], v[76:79], v[28:31]
	v_mfma_f32_16x16x32_bf16 v[24:27], v[246:249], v[230:233], v[24:27]
	v_mfma_f32_16x16x32_bf16 v[20:23], v[246:249], v[238:241], v[20:23]
	v_mfma_f32_16x16x32_bf16 v[8:11], v[194:197], v[72:75], v[8:11]
	v_mfma_f32_16x16x32_bf16 v[28:31], v[194:197], v[80:83], v[28:31]
	v_mfma_f32_16x16x32_bf16 v[24:27], v[194:197], v[234:237], v[24:27]
	v_mfma_f32_16x16x32_bf16 v[20:23], v[194:197], v[242:245], v[20:23]
	v_mfma_f32_16x16x32_bf16 v[16:19], v[222:225], v[60:63], v[16:19]
	v_mfma_f32_16x16x32_bf16 v[12:15], v[222:225], v[76:79], v[12:15]
	v_mfma_f32_16x16x32_bf16 v[4:7], v[222:225], v[230:233], v[4:7]
	v_mfma_f32_16x16x32_bf16 v[0:3], v[222:225], v[238:241], v[0:3]
	v_mfma_f32_16x16x32_bf16 v[16:19], v[84:87], v[72:75], v[16:19]
	v_mfma_f32_16x16x32_bf16 v[12:15], v[84:87], v[80:83], v[12:15]
	v_mfma_f32_16x16x32_bf16 v[4:7], v[84:87], v[234:237], v[4:7]
	v_mfma_f32_16x16x32_bf16 v[0:3], v[84:87], v[242:245], v[0:3]
	v_cvt_pk_bf16_f32 v56, v56, v57
	v_cvt_pk_bf16_f32 v57, v58, v59
	v_lshl_add_u64 v[58:59], v[88:89], 1, v[198:199]
	global_store_dwordx2 v[58:59], v[56:57], off
	v_cvt_pk_bf16_f32 v52, v52, v53
	v_cvt_pk_bf16_f32 v53, v54, v55
	v_lshl_add_u64 v[54:55], v[100:101], 1, v[198:199]
	global_store_dwordx2 v[54:55], v[52:53], off
	v_cvt_pk_bf16_f32 v60, v8, v9
	v_cvt_pk_bf16_f32 v61, v10, v11
	v_cvt_pk_bf16_f32 v62, v28, v29
	v_cvt_pk_bf16_f32 v63, v30, v31
	ds_write2st64_b64 v177, v[60:61], v[62:63] offset1:16
	v_cvt_pk_bf16_f32 v72, v24, v25
	v_cvt_pk_bf16_f32 v73, v26, v27
	v_cvt_pk_bf16_f32 v74, v20, v21
	v_cvt_pk_bf16_f32 v75, v22, v23
	ds_write2st64_b64 v177, v[72:73], v[74:75] offset0:32 offset1:48
	v_cvt_pk_bf16_f32 v76, v16, v17
	v_cvt_pk_bf16_f32 v77, v18, v19
	v_cvt_pk_bf16_f32 v78, v12, v13
	v_cvt_pk_bf16_f32 v79, v14, v15
	ds_write2st64_b64 v178, v[76:77], v[78:79] offset1:16
	v_cvt_pk_bf16_f32 v80, v4, v5
	v_cvt_pk_bf16_f32 v81, v6, v7
	v_cvt_pk_bf16_f32 v82, v0, v1
	v_cvt_pk_bf16_f32 v83, v2, v3
	ds_write2st64_b64 v178, v[80:81], v[82:83] offset0:32 offset1:48
	s_add_i32 s48, s48, -1
	s_cmp_eq_u32 s48, -1
	s_waitcnt lgkmcnt(0)
	s_barrier
; #define LAS __attribute__((address_space(3)))
; DI unsigned pk2(float lo, float hi) { const f32x2 v = {lo, hi}; const hbf16x2 b = __builtin_convertvector(v, hbf16x2); return __builtin_bit_cast(unsigned, b); }
; #define LDS_BARRIER() do { asm volatile("s_waitcnt lgkmcnt(0)" ::: "memory"); __builtin_amdgcn_s_barrier(); } while (0)
; DI void ret_chain_phase(const Ctx& a, LAS unsigned char* lds) {
;     ...
;             const int row0 = RC_ROW0(s);
; #pragma unroll
;             for (int k = 0; k < 4; ++k) { const int p = tid + k * NTHREADS; const int d = p >> 3, ch = p & 7;
;                 *(LAS u32x4*)(lds + RC_SKT + d * 128 + ((ch ^ ((d >> 1) & 7)) << 4)) = pkt[k]; }
;             { const int v_ = tid >> 3, ch = tid & 7;
;                 *(LAS u32x4*)(lds + RC_SVT + v_ * 128 + ((ch ^ ((v_ >> 1) & 7)) << 4)) = pvt; }
;             asm volatile("s_waitcnt vmcnt(0)" ::: "memory");
;             if (s + 1 < 68) RC_ISSUE(s + 1);
;             LDS_BARRIER();
;             int frx = fr; asm volatile("" : "+v"(frx));
;             const int sw5 = frx * 512, sw1 = frx * 128, kx = (frx >> 1) & 7;
;     ...
;             bf16x8 qf[8];
; #pragma unroll
;             for (int ks = 0; ks < 8; ++ks) qf[ks] = *(const LAS bf16x8*)(lds + A512(RC_SQ, it, ks));
; #pragma unroll
;             for (int j2 = 0; j2 < 2; ++j2) {
;                 const int jt = 2 * half + j2;
;                 f32x4 acc = (f32x4){0.f, 0.f, 0.f, 0.f};
; #pragma unroll
;                 for (int ks = 0; ks < 8; ++ks) { const bf16x8 kf = *(const LAS bf16x8*)(lds + A512(RC_SK, jt, ks)); acc = MFMA16(kf, qf[ks], acc); }
;                 float pv[4];
; #pragma unroll
;                 for (int r = 0; r < 4; ++r) pv[r] = acc[r] * wdec[j2][r];
;                 u32x2 w; w.x = pk2(pv[0], pv[1]); w.y = pk2(pv[2], pv[3]);
;                 *(LAS u32x2*)(lds + RC_SP + icol * 128 + (((2 * jt + (fq >> 1)) ^ ((icol >> 1) & 7)) << 4) + (fq & 1) * 8) = w;
;             }
;             f32x4 accO[2];
; #pragma unroll
;             for (int vv = 0; vv < 2; ++vv) {
;                 f32x4 acc = (f32x4){0.f, 0.f, 0.f, 0.f};
; #pragma unroll
;                 for (int ks = 0; ks < 8; ++ks) { const bf16x8 sf = *(const LAS bf16x8*)(lds + A512(RC_SS, 2 * half + vv, ks)); acc = MFMA16(sf, qf[ks], acc); }
;                 accO[vv] = acc * qdec;
;             }
	s_cbranch_scc0 .LBB0_199
	s_waitcnt vmcnt(0)
	ds_write_b128 v173, v[32:35]
	ds_write_b128 v173, v[36:39] offset:8192
	ds_write_b128 v173, v[40:43] offset:16384
	ds_write_b128 v173, v[44:47] offset:24576
	ds_write_b128 v174, v[48:51]
	s_waitcnt vmcnt(0)
	v_mov_b32_e32 v64, v120
	s_waitcnt lgkmcnt(0)
	s_barrier
	s_and_b64 s[20:21], s[42:43], exec
	v_lshlrev_b32_e32 v74, 9, v64
	v_xor_b32_e32 v33, v64, v121
	v_add_u32_e32 v32, v126, v74
	v_lshlrev_b32_e32 v75, 4, v33
	v_add_u32_e32 v33, v32, v75
	ds_read_b128 v[60:63], v33
	v_xor_b32_e32 v33, v64, v129
	v_lshlrev_b32_e32 v76, 4, v33
	v_add_u32_e32 v83, v127, v74
	v_add_u32_e32 v33, v32, v76
	v_add_u32_e32 v70, v83, v76
	ds_read_b128 v[56:59], v33
	ds_read_b128 v[70:73], v70 offset:32768
	v_xor_b32_e32 v33, v64, v157
	v_lshlrev_b32_e32 v77, 4, v33
	v_add_u32_e32 v33, v32, v77
	ds_read_b128 v[52:55], v33
	v_xor_b32_e32 v33, v64, v158
	v_lshlrev_b32_e32 v78, 4, v33
	v_add_u32_e32 v33, v32, v78
	ds_read_b128 v[48:51], v33
	v_xor_b32_e32 v33, v64, v159
	v_lshlrev_b32_e32 v79, 4, v33
	v_add_u32_e32 v33, v32, v79
	ds_read_b128 v[44:47], v33
	v_xor_b32_e32 v33, v64, v160
	v_lshlrev_b32_e32 v80, 4, v33
	v_add_u32_e32 v33, v32, v80
	ds_read_b128 v[40:43], v33
	v_xor_b32_e32 v33, v64, v161
	v_lshlrev_b32_e32 v81, 4, v33
	v_add_u32_e32 v33, v32, v81
	ds_read_b128 v[36:39], v33
	v_xor_b32_e32 v33, v64, v162
	v_lshlrev_b32_e32 v82, 4, v33
	v_add_u32_e32 v32, v32, v82
	v_add_u32_e32 v66, v83, v75
	ds_read_b128 v[32:35], v32
	ds_read_b128 v[66:69], v66 offset:32768
	s_waitcnt lgkmcnt(0)
	v_mfma_f32_16x16x32_bf16 v[66:69], v[66:69], v[60:63], 0
	s_cselect_b32 s30, 0xfc0, 0
	v_lshrrev_b32_e32 v65, 1, v64
	v_lshlrev_b32_e32 v64, 7, v64
	v_mfma_f32_16x16x32_bf16 v[66:69], v[70:73], v[56:59], v[66:69]
	v_add_u32_e32 v70, v83, v77
	ds_read_b128 v[70:73], v70 offset:32768
	v_pk_mul_f32 v[10:11], v[104:105], v[10:11]
	s_waitcnt lgkmcnt(0)
	v_mfma_f32_16x16x32_bf16 v[66:69], v[70:73], v[52:55], v[66:69]
	v_add_u32_e32 v70, v83, v78
	ds_read_b128 v[70:73], v70 offset:32768
	v_pk_mul_f32 v[8:9], v[106:107], v[8:9]
	s_waitcnt lgkmcnt(0)
	v_mfma_f32_16x16x32_bf16 v[66:69], v[70:73], v[48:51], v[66:69]
	v_add_u32_e32 v70, v83, v79
	ds_read_b128 v[70:73], v70 offset:32768
	v_pk_mul_f32 v[18:19], v[104:105], v[18:19]
	s_waitcnt lgkmcnt(0)
	v_mfma_f32_16x16x32_bf16 v[66:69], v[70:73], v[44:47], v[66:69]
	v_add_u32_e32 v70, v83, v80
	ds_read_b128 v[70:73], v70 offset:32768
	v_pk_mul_f32 v[16:17], v[106:107], v[16:17]
	s_waitcnt lgkmcnt(0)
	v_mfma_f32_16x16x32_bf16 v[66:69], v[70:73], v[40:43], v[66:69]
	v_add_u32_e32 v70, v83, v81
	ds_read_b128 v[70:73], v70 offset:32768
	v_pk_mul_f32 v[14:15], v[104:105], v[14:15]
	s_waitcnt lgkmcnt(0)
	v_mfma_f32_16x16x32_bf16 v[66:69], v[70:73], v[36:39], v[66:69]
	v_add_u32_e32 v70, v83, v82
	ds_read_b128 v[70:73], v70 offset:32768
	v_add_u32_e32 v83, v163, v74
	s_waitcnt lgkmcnt(0)
	v_mfma_f32_16x16x32_bf16 v[66:69], v[70:73], v[32:35], v[66:69]
	v_add_u32_e32 v70, v83, v76
	v_pk_mul_f32 v[12:13], v[106:107], v[12:13]
	v_pk_mul_f32 v[6:7], v[104:105], v[6:7]
	s_nop 4
	v_mul_f32_e32 v66, v179, v66
	v_mul_f32_e32 v67, v180, v67
	v_mul_f32_e32 v68, v185, v68
	v_mul_f32_e32 v69, v186, v69
	v_cvt_pk_bf16_f32 v66, v66, v67
	v_cvt_pk_bf16_f32 v67, v68, v69
	ds_write_b64 v175, v[66:67]
	v_add_u32_e32 v66, v83, v75
	ds_read_b128 v[66:69], v66 offset:32768
	ds_read_b128 v[70:73], v70 offset:32768
	s_waitcnt lgkmcnt(1)
	v_mfma_f32_16x16x32_bf16 v[66:69], v[66:69], v[60:63], 0
	v_mul_f32_e64 v4, v106, v4
	v_mul_f32_e64 v5, v107, v5
	v_pk_mul_f32 v[2:3], v[104:105], v[2:3]
	v_pk_mul_f32 v[0:1], v[106:107], v[0:1]
	s_waitcnt lgkmcnt(0)
	v_mfma_f32_16x16x32_bf16 v[66:69], v[70:73], v[56:59], v[66:69]
	v_add_u32_e32 v70, v83, v77
	ds_read_b128 v[70:73], v70 offset:32768
	v_readlane_b32 s0, v254, 45
	s_waitcnt lgkmcnt(0)
	v_mfma_f32_16x16x32_bf16 v[66:69], v[70:73], v[52:55], v[66:69]
	v_add_u32_e32 v70, v83, v78
	ds_read_b128 v[70:73], v70 offset:32768
	s_add_i32 s3, s3, s0
	s_waitcnt lgkmcnt(0)
	v_mfma_f32_16x16x32_bf16 v[66:69], v[70:73], v[48:51], v[66:69]
	v_add_u32_e32 v70, v83, v79
	ds_read_b128 v[70:73], v70 offset:32768
	s_cmpk_gt_i32 s3, 0xff
	s_waitcnt lgkmcnt(0)
	v_mfma_f32_16x16x32_bf16 v[66:69], v[70:73], v[44:47], v[66:69]
	v_add_u32_e32 v70, v83, v80
	ds_read_b128 v[70:73], v70 offset:32768
	v_readlane_b32 s49, v255, 19
	s_waitcnt lgkmcnt(0)
	v_mfma_f32_16x16x32_bf16 v[66:69], v[70:73], v[40:43], v[66:69]
	v_add_u32_e32 v70, v83, v81
	ds_read_b128 v[70:73], v70 offset:32768
	s_mov_b64 s[50:51], s[4:5]
	s_waitcnt lgkmcnt(0)
	v_mfma_f32_16x16x32_bf16 v[66:69], v[70:73], v[36:39], v[66:69]
	v_add_u32_e32 v70, v83, v82
	ds_read_b128 v[70:73], v70 offset:32768
	v_add_u32_e32 v83, v164, v74
	s_waitcnt lgkmcnt(0)
	v_mfma_f32_16x16x32_bf16 v[66:69], v[70:73], v[32:35], v[66:69]
	v_add_u32_e32 v70, v83, v76
	v_add_u32_e32 v74, v165, v74
	s_nop 5
	v_mul_f32_e32 v66, v181, v66
	v_mul_f32_e32 v67, v182, v67
	v_mul_f32_e32 v68, v183, v68
	v_mul_f32_e32 v69, v184, v69
	v_cvt_pk_bf16_f32 v66, v66, v67
	v_cvt_pk_bf16_f32 v67, v68, v69
	ds_write_b64 v176, v[66:67]
	v_add_u32_e32 v66, v83, v75
	ds_read_b128 v[66:69], v66
	ds_read_b128 v[70:73], v70
	s_waitcnt lgkmcnt(1)
	v_mfma_f32_16x16x32_bf16 v[66:69], v[66:69], v[60:63], 0
	s_waitcnt lgkmcnt(0)
	v_mfma_f32_16x16x32_bf16 v[66:69], v[70:73], v[56:59], v[66:69]
	v_add_u32_e32 v70, v83, v77
	ds_read_b128 v[70:73], v70
	s_waitcnt lgkmcnt(0)
	v_mfma_f32_16x16x32_bf16 v[66:69], v[70:73], v[52:55], v[66:69]
	v_add_u32_e32 v70, v83, v78
	ds_read_b128 v[70:73], v70
	s_waitcnt lgkmcnt(0)
; #define LAS __attribute__((address_space(3)))
; DI void ret_chain_phase(const Ctx& a, LAS unsigned char* lds) {
;     ...
;             f32x4 accO[2];
; #pragma unroll
;             for (int vv = 0; vv < 2; ++vv) {
;                 f32x4 acc = (f32x4){0.f, 0.f, 0.f, 0.f};
; #pragma unroll
;                 for (int ks = 0; ks < 8; ++ks) { const bf16x8 sf = *(const LAS bf16x8*)(lds + A512(RC_SS, 2 * half + vv, ks)); acc = MFMA16(sf, qf[ks], acc); }
;                 accO[vv] = acc * qdec;
;             }
;             LDS_BARRIER();
;             if (s + 1 < 68) RC_DMA_QK(s + 1);
; #pragma unroll
;             for (int vv = 0; vv < 2; ++vv) {
;                 const int vt = 2 * half + vv;
; #pragma unroll
;                 for (int k2 = 0; k2 < 2; ++k2) {
;                     const bf16x8 vf = *(const LAS bf16x8*)(lds + A128(RC_SVT, vt, k2));
;                     const bf16x8 pf = *(const LAS bf16x8*)(lds + A128(RC_SP, it, k2));
;                     accO[vv] = MFMA16(vf, pf, accO[vv]);
;                 }
;                 u32x2 w; w.x = pk2(accO[vv][0], accO[vv][1]); w.y = pk2(accO[vv][2], accO[vv][3]);
;                 *(u32x2*)(O + (size_t)(row0 + icol) * 2048 + h * 512 + vs * 64 + 16 * vt + 4 * fq) = w;
;             }
;             bf16x8 vfr[4][2];
; #pragma unroll
;             for (int vt = 0; vt < 4; ++vt) { vfr[vt][0] = *(const LAS bf16x8*)(lds + A128(RC_SVT, vt, 0)); vfr[vt][1] = *(const LAS bf16x8*)(lds + A128(RC_SVT, vt, 1)); }
; #pragma unroll
;             for (int di = 0; di < 2; ++di) {
;                 const int dt = 2 * wid + di;
;                 bf16x8 kt[2];
; #pragma unroll
;                 for (int k2 = 0; k2 < 2; ++k2) kt[k2] = *(const LAS bf16x8*)(lds + A128(RC_SKT, dt, k2));
; #pragma unroll
;                 for (int vt = 0; vt < 4; ++vt) {
;                     f32x4 sacc = accS[di][vt] * cdec;
;                     sacc = MFMA16(kt[0], vfr[vt][0], sacc); sacc = MFMA16(kt[1], vfr[vt][1], sacc);
;                     accS[di][vt] = sacc;
;                     const int v_ = 16 * vt + fr;
;                     u32x2 w; w.x = pk2(sacc[0], sacc[1]); w.y = pk2(sacc[2], sacc[3]);
;                     *(LAS u32x2*)(lds + RC_SS + v_ * 512 + (((2 * dt + (fq >> 1)) ^ (v_ & 15)) << 4) + (fq & 1) * 8) = w;
;                 }
;             }
;             LDS_BARRIER();
;         }
;     }
	v_mfma_f32_16x16x32_bf16 v[66:69], v[70:73], v[48:51], v[66:69]
	v_add_u32_e32 v70, v83, v79
	ds_read_b128 v[70:73], v70
	s_waitcnt lgkmcnt(0)
	v_mfma_f32_16x16x32_bf16 v[66:69], v[70:73], v[44:47], v[66:69]
	v_add_u32_e32 v70, v83, v80
	ds_read_b128 v[70:73], v70
	s_waitcnt lgkmcnt(0)
	v_mfma_f32_16x16x32_bf16 v[66:69], v[70:73], v[40:43], v[66:69]
	v_add_u32_e32 v70, v83, v81
	ds_read_b128 v[70:73], v70
	s_waitcnt lgkmcnt(0)
	v_mfma_f32_16x16x32_bf16 v[66:69], v[70:73], v[36:39], v[66:69]
	v_add_u32_e32 v70, v83, v82
	ds_read_b128 v[70:73], v70
	s_waitcnt lgkmcnt(0)
	v_mfma_f32_16x16x32_bf16 v[66:69], v[70:73], v[32:35], v[66:69]
	v_add_u32_e32 v70, v74, v75
	ds_read_b128 v[70:73], v70
	s_nop 5
	v_pk_mul_f32 v[68:69], v[112:113], v[68:69]
	s_waitcnt lgkmcnt(0)
	v_mfma_f32_16x16x32_bf16 v[60:63], v[70:73], v[60:63], 0
	v_add_u32_e32 v70, v74, v76
	ds_read_b128 v[70:73], v70
	v_pk_mul_f32 v[66:67], v[110:111], v[66:67]
	s_waitcnt lgkmcnt(0)
	v_mfma_f32_16x16x32_bf16 v[56:59], v[70:73], v[56:59], v[60:63]
	s_nop 2
	v_add_u32_e32 v60, v74, v77
	ds_read_b128 v[60:63], v60
	v_add_u32_e32 v70, v168, v64
	s_waitcnt lgkmcnt(0)
	v_mfma_f32_16x16x32_bf16 v[52:55], v[60:63], v[52:55], v[56:59]
	s_nop 2
	v_add_u32_e32 v56, v74, v78
	ds_read_b128 v[56:59], v56
	s_waitcnt lgkmcnt(0)
	v_mfma_f32_16x16x32_bf16 v[48:51], v[56:59], v[48:51], v[52:55]
	s_nop 2
	v_add_u32_e32 v52, v74, v79
	ds_read_b128 v[52:55], v52
	s_waitcnt lgkmcnt(0)
	v_mfma_f32_16x16x32_bf16 v[44:47], v[52:55], v[44:47], v[48:51]
	s_nop 2
	v_add_u32_e32 v48, v74, v80
	ds_read_b128 v[48:51], v48
	s_waitcnt lgkmcnt(0)
	v_mfma_f32_16x16x32_bf16 v[40:43], v[48:51], v[40:43], v[44:47]
	s_nop 2
	v_add_u32_e32 v44, v74, v81
	ds_read_b128 v[44:47], v44
	v_add_u32_e32 v48, v128, v64
	s_waitcnt lgkmcnt(0)
	v_mfma_f32_16x16x32_bf16 v[36:39], v[44:47], v[36:39], v[40:43]
	s_nop 2
	v_add_u32_e32 v40, v74, v82
	ds_read_b128 v[40:43], v40
	v_add_u32_e32 v44, v166, v64
	s_waitcnt lgkmcnt(0)
	v_mfma_f32_16x16x32_bf16 v[32:35], v[40:43], v[32:35], v[36:39]
	s_nop 2
	v_or_b32_e32 v36, s30, v122
	v_or_b32_e32 v36, s44, v36
	v_ashrrev_i32_e32 v37, 31, v36
	v_lshlrev_b64 v[36:37], 12, v[36:37]
	v_lshl_add_u64 v[52:53], v[108:109], 0, v[36:37]
	v_bitop3_b32 v36, v65, v121, 7 bitop3:0x6c
	v_lshlrev_b32_e32 v76, 4, v36
	v_add_u32_e32 v36, v44, v76
	s_waitcnt lgkmcnt(0)
	s_barrier
	ds_read_b128 v[36:39], v36
	v_bitop3_b32 v45, v65, v129, 7 bitop3:0x6c
	v_lshlrev_b32_e32 v65, 4, v45
	v_add_u32_e32 v40, v48, v76
	v_add_u32_e32 v44, v44, v65
	ds_read_b128 v[40:43], v40
	ds_read_b128 v[44:47], v44
	v_add_u32_e32 v48, v48, v65
	ds_read_b128 v[48:51], v48
	s_waitcnt lgkmcnt(2)
	v_mfma_f32_16x16x32_bf16 v[36:39], v[36:39], v[40:43], v[66:69]
	v_mul_f32_e64 v34, v112, v34
	v_mul_f32_e64 v35, v113, v35
	v_pk_mul_f32 v[32:33], v[110:111], v[32:33]
	v_add_u32_e32 v66, v70, v76
	s_waitcnt lgkmcnt(0)
	v_mfma_f32_16x16x32_bf16 v[36:39], v[44:47], v[48:51], v[36:39]
	v_add_u32_e32 v44, v167, v64
	v_add_u32_e32 v70, v70, v65
	ds_read_b128 v[66:69], v66
	ds_read_b128 v[70:73], v70
	s_nop 3
	v_cvt_pk_bf16_f32 v36, v36, v37
	v_cvt_pk_bf16_f32 v37, v38, v39
	v_lshl_add_u64 v[38:39], v[88:89], 1, v[52:53]
	global_store_dwordx2 v[38:39], v[36:37], off
	v_add_u32_e32 v36, v44, v76
	ds_read_b128 v[36:39], v36
	s_waitcnt lgkmcnt(0)
	v_mfma_f32_16x16x32_bf16 v[32:35], v[36:39], v[40:43], v[32:35]
	v_add_u32_e32 v36, v44, v65
	ds_read_b128 v[36:39], v36
	s_waitcnt lgkmcnt(0)
	v_mfma_f32_16x16x32_bf16 v[32:35], v[36:39], v[48:51], v[32:35]
	s_nop 7
	v_cvt_pk_bf16_f32 v32, v32, v33
	v_cvt_pk_bf16_f32 v33, v34, v35
	v_lshl_add_u64 v[34:35], v[100:101], 1, v[52:53]
	global_store_dwordx2 v[34:35], v[32:33], off
	v_add_u32_e32 v32, s2, v64
	v_add_u32_e32 v33, v32, v76
	v_add_u32_e32 v32, v32, v65
	ds_read_b128 v[60:63], v33
	ds_read_b128 v[56:59], v32
	v_add_u32_e32 v32, s84, v64
	v_add_u32_e32 v33, v32, v76
	v_add_u32_e32 v32, v32, v65
	ds_read_b128 v[52:55], v33
	ds_read_b128 v[48:51], v32
	v_add_u32_e32 v32, s85, v64
	v_add_u32_e32 v33, v32, v76
	v_add_u32_e32 v32, v32, v65
	ds_read_b128 v[44:47], v33
	ds_read_b128 v[40:43], v32
	v_add_u32_e32 v32, s24, v64
	v_add_u32_e32 v33, v32, v76
	v_add_u32_e32 v32, v32, v65
	ds_read_b128 v[36:39], v33
	ds_read_b128 v[32:35], v32
	s_waitcnt lgkmcnt(7)
	v_mfma_f32_16x16x32_bf16 v[8:11], v[66:69], v[60:63], v[8:11]
	s_waitcnt lgkmcnt(6)
	v_mfma_f32_16x16x32_bf16 v[8:11], v[70:73], v[56:59], v[8:11]
	s_nop 7
	v_cvt_pk_bf16_f32 v74, v8, v9
	v_cvt_pk_bf16_f32 v75, v10, v11
	v_pk_mul_f32 v[10:11], v[104:105], v[30:31]
	v_pk_mul_f32 v[8:9], v[106:107], v[28:29]
	s_waitcnt lgkmcnt(5)
	s_nop 0
	v_mfma_f32_16x16x32_bf16 v[8:11], v[66:69], v[52:55], v[8:11]
	s_waitcnt lgkmcnt(4)
	v_mfma_f32_16x16x32_bf16 v[8:11], v[70:73], v[48:51], v[8:11]
	s_nop 7
	v_cvt_pk_bf16_f32 v8, v8, v9
	v_cvt_pk_bf16_f32 v9, v10, v11
	ds_write2st64_b64 v177, v[74:75], v[8:9] offset1:16
	v_pk_mul_f32 v[10:11], v[104:105], v[26:27]
	v_pk_mul_f32 v[8:9], v[106:107], v[24:25]
	s_waitcnt lgkmcnt(4)
	s_nop 0
	v_mfma_f32_16x16x32_bf16 v[8:11], v[66:69], v[44:47], v[8:11]
	s_waitcnt lgkmcnt(3)
	v_mfma_f32_16x16x32_bf16 v[8:11], v[70:73], v[40:43], v[8:11]
	s_nop 7
	v_cvt_pk_bf16_f32 v24, v8, v9
	v_cvt_pk_bf16_f32 v25, v10, v11
	v_pk_mul_f32 v[10:11], v[104:105], v[22:23]
	v_pk_mul_f32 v[8:9], v[106:107], v[20:21]
	v_add_u32_e32 v20, v169, v64
	s_waitcnt lgkmcnt(2)
	v_mfma_f32_16x16x32_bf16 v[8:11], v[66:69], v[36:39], v[8:11]
	s_waitcnt lgkmcnt(1)
	v_mfma_f32_16x16x32_bf16 v[8:11], v[70:73], v[32:35], v[8:11]
	s_nop 7
	v_cvt_pk_bf16_f32 v8, v8, v9
	v_cvt_pk_bf16_f32 v9, v10, v11
	ds_write2st64_b64 v177, v[24:25], v[8:9] offset0:32 offset1:48
	v_add_u32_e32 v8, v20, v76
	ds_read_b128 v[8:11], v8
	v_add_u32_e32 v20, v20, v65
	ds_read_b128 v[20:23], v20
	s_waitcnt lgkmcnt(1)
	v_mfma_f32_16x16x32_bf16 v[16:19], v[8:11], v[60:63], v[16:19]
	v_mfma_f32_16x16x32_bf16 v[12:15], v[8:11], v[52:55], v[12:15]
	v_mfma_f32_16x16x32_bf16 v[4:7], v[8:11], v[44:47], v[4:7]
	v_mfma_f32_16x16x32_bf16 v[0:3], v[8:11], v[36:39], v[0:3]
	s_waitcnt lgkmcnt(0)
	v_mfma_f32_16x16x32_bf16 v[16:19], v[20:23], v[56:59], v[16:19]
	v_mfma_f32_16x16x32_bf16 v[12:15], v[20:23], v[48:51], v[12:15]
	v_mfma_f32_16x16x32_bf16 v[4:7], v[20:23], v[40:43], v[4:7]
	s_nop 5
	v_cvt_pk_bf16_f32 v16, v16, v17
	v_cvt_pk_bf16_f32 v17, v18, v19
	v_cvt_pk_bf16_f32 v12, v12, v13
	v_mfma_f32_16x16x32_bf16 v[0:3], v[20:23], v[32:35], v[0:3]
	v_cvt_pk_bf16_f32 v13, v14, v15
	v_cvt_pk_bf16_f32 v4, v4, v5
	v_cvt_pk_bf16_f32 v5, v6, v7
	ds_write2st64_b64 v178, v[16:17], v[12:13] offset1:16
	s_nop 3
	v_cvt_pk_bf16_f32 v0, v0, v1
	v_cvt_pk_bf16_f32 v1, v2, v3
	ds_write2st64_b64 v178, v[4:5], v[0:1] offset0:32 offset1:48
	s_waitcnt lgkmcnt(0)
	s_barrier
	s_cbranch_scc0 .LBB0_195
